# GEMM K-loop: waves 4-7 run a copy of the loop with a static s_setprio 1 (no per-phase flips)
# baseline (speedup 1.0000x reference)
; #define S_STAGE(bufoff, gbase, voff) do { _Pragma("unroll") for (int _i = 0; _i < 2; ++_i) \
;     __builtin_amdgcn_global_load_lds((const unsigned*)((gbase) + (voff)[_i]), (LAS unsigned*)(lds + (bufoff) + ldsw + _i * 8192), 16, 0, 0); } while (0)
; #define S_LDA(dst, b, h) do { _Pragma("unroll") for (int m = 0; m < 4; ++m) _Pragma("unroll") for (int k = 0; k < 2; ++k) dst[m][k] = *(const LAS bf16x8*)(lds + S_SA(b, h) + aoff + m * 2048 + k * 1024); } while (0)
; #define S_LDB(dst, b, h) do { _Pragma("unroll") for (int n = 0; n < 2; ++n) _Pragma("unroll") for (int k = 0; k < 2; ++k) dst[n][k] = *(const LAS bf16x8*)(lds + S_SB(b, h) + boff + n * 2048 + k * 1024); } while (0)
; #define S_SCHED __builtin_amdgcn_sched_barrier(0)
; DI void gemm_phase(LAS unsigned char* lds, const GemmDesc& d, float* __restrict__ X) {
;     ...
;     for (int t = 0; t < nt; t += 2) {
;       const bool last = (t == nt - 2);
;       const char* a1 = cA + (size_t)(t + 1) * kstepA;
;       const char* a2 = last ? nA : cA + (size_t)(t + 2) * kstepA; const char* b2 = last ? nB : cB + (size_t)(t + 2) * kstepB;
;       const char* a3 = a2 + kstepA; const char* b3 = b2 + kstepB;
;       S_LDB(B0, 0, 0); S_LDB(B1, 0, 1); S_SCHED; S_LDA(At, 0, 0); S_STAGE(S_SA(1, 1), a1 + hstepA, voffA);
;     ...
; #pragma unroll
;     for (int a = 0; a < 2; ++a)
; #pragma unroll
;       for (int b = 0; b < 2; ++b)
; #pragma unroll
;         for (int m = 0; m < 4; ++m)
; #pragma unroll
;           for (int n = 0; n < 2; ++n) acc[a][b][m][n] = (f32x4){0.f, 0.f, 0.f, 0.f};
;     pm = pm2; pn = pn2; cA = nA; cB = nB;
.LBB0_345:
	s_or_b64 exec, exec, s[78:79]
	s_add_u32 s20, s88, s27
	s_addc_u32 s21, s89, 0
	s_add_u32 s64, s90, 0x100
	v_mov_b32_e32 v2, 0
	s_addc_u32 s69, s91, 0
	s_mov_b64 s[90:91], 0
	v_mov_b32_e32 v3, v2
	v_mov_b32_e32 v4, v2
	v_mov_b32_e32 v5, v2
	v_mov_b32_e32 v6, v2
	v_mov_b32_e32 v7, v2
	v_mov_b32_e32 v8, v2
	v_mov_b32_e32 v9, v2
	v_mov_b32_e32 v18, v2
	v_mov_b32_e32 v19, v2
	v_mov_b32_e32 v20, v2
	v_mov_b32_e32 v21, v2
	v_mov_b32_e32 v22, v2
	v_mov_b32_e32 v23, v2
	v_mov_b32_e32 v24, v2
	v_mov_b32_e32 v25, v2
	v_mov_b32_e32 v34, v2
	v_mov_b32_e32 v35, v2
	v_mov_b32_e32 v36, v2
	v_mov_b32_e32 v37, v2
	v_mov_b32_e32 v38, v2
	v_mov_b32_e32 v39, v2
	v_mov_b32_e32 v40, v2
	v_mov_b32_e32 v41, v2
	v_mov_b32_e32 v50, v2
	v_mov_b32_e32 v51, v2
	v_mov_b32_e32 v52, v2
	v_mov_b32_e32 v53, v2
	v_mov_b32_e32 v54, v2
	v_mov_b32_e32 v55, v2
	v_mov_b32_e32 v56, v2
	v_mov_b32_e32 v57, v2
	v_mov_b32_e32 v10, v2
	v_mov_b32_e32 v11, v2
	v_mov_b32_e32 v12, v2
	v_mov_b32_e32 v13, v2
	s_waitcnt vmcnt(0)
	v_mov_b32_e32 v14, v2
	v_mov_b32_e32 v15, v2
	v_mov_b32_e32 v16, v2
	v_mov_b32_e32 v17, v2
	v_mov_b32_e32 v26, v2
	v_mov_b32_e32 v27, v2
	v_mov_b32_e32 v28, v2
	v_mov_b32_e32 v29, v2
	v_mov_b32_e32 v30, v2
	v_mov_b32_e32 v31, v2
	v_mov_b32_e32 v32, v2
	v_mov_b32_e32 v33, v2
	v_mov_b32_e32 v42, v2
	v_mov_b32_e32 v43, v2
	v_mov_b32_e32 v44, v2
	v_mov_b32_e32 v45, v2
	v_mov_b32_e32 v46, v2
	v_mov_b32_e32 v47, v2
	v_mov_b32_e32 v48, v2
	v_mov_b32_e32 v49, v2
	v_mov_b32_e32 v58, v2
	v_mov_b32_e32 v59, v2
	v_mov_b32_e32 v60, v2
	v_mov_b32_e32 v61, v2
	v_mov_b32_e32 v62, v2
	v_mov_b32_e32 v63, v2
	v_mov_b32_e32 v64, v2
	v_mov_b32_e32 v65, v2
	v_mov_b32_e32 v66, v2
	v_mov_b32_e32 v67, v2
	v_mov_b32_e32 v68, v2
	v_mov_b32_e32 v69, v2
	v_mov_b32_e32 v70, v2
	v_mov_b32_e32 v71, v2
	v_mov_b32_e32 v72, v2
	v_mov_b32_e32 v73, v2
	v_mov_b32_e32 v82, v2
	v_mov_b32_e32 v83, v2
	v_mov_b32_e32 v84, v2
	v_mov_b32_e32 v85, v2
	v_mov_b32_e32 v86, v2
	v_mov_b32_e32 v87, v2
	v_mov_b32_e32 v88, v2
	v_mov_b32_e32 v89, v2
	v_mov_b32_e32 v98, v2
	v_mov_b32_e32 v99, v2
	v_mov_b32_e32 v100, v2
	v_mov_b32_e32 v101, v2
	v_mov_b32_e32 v102, v2
	v_mov_b32_e32 v103, v2
	v_mov_b32_e32 v104, v2
	v_mov_b32_e32 v105, v2
	v_mov_b32_e32 v114, v2
	v_mov_b32_e32 v115, v2
	v_mov_b32_e32 v116, v2
	v_mov_b32_e32 v117, v2
	v_mov_b32_e32 v118, v2
	v_mov_b32_e32 v119, v2
	v_mov_b32_e32 v120, v2
	v_mov_b32_e32 v121, v2
	v_mov_b32_e32 v74, v2
	v_mov_b32_e32 v75, v2
	v_mov_b32_e32 v76, v2
	v_mov_b32_e32 v77, v2
	v_mov_b32_e32 v78, v2
	v_mov_b32_e32 v79, v2
	v_mov_b32_e32 v80, v2
	v_mov_b32_e32 v81, v2
	v_mov_b32_e32 v90, v2
	v_mov_b32_e32 v91, v2
	v_mov_b32_e32 v92, v2
	v_mov_b32_e32 v93, v2
	v_mov_b32_e32 v94, v2
	v_mov_b32_e32 v95, v2
	v_mov_b32_e32 v96, v2
	v_mov_b32_e32 v97, v2
	v_mov_b32_e32 v106, v2
	v_mov_b32_e32 v107, v2
	v_mov_b32_e32 v108, v2
	v_mov_b32_e32 v109, v2
	v_mov_b32_e32 v110, v2
	v_mov_b32_e32 v111, v2
	v_mov_b32_e32 v112, v2
	v_mov_b32_e32 v113, v2
	v_mov_b32_e32 v122, v2
	v_mov_b32_e32 v123, v2
	v_mov_b32_e32 v124, v2
	v_mov_b32_e32 v125, v2
	v_mov_b32_e32 v126, v2
	v_mov_b32_e32 v127, v2
	v_mov_b32_e32 v128, v2
	v_mov_b32_e32 v129, v2
	s_cmp_lg_u32 s32, 0
	s_cbranch_scc1 .Lgemm_h1
.LBB0_346:
	s_add_u32 s14, s90, 1
	s_addc_u32 s15, s91, 0
	s_add_u32 vcc_lo, s90, 2
	s_addc_u32 vcc_hi, s91, 0
	s_lshl_b64 s[78:79], vcc, s8
	s_add_u32 s56, s88, s78
	s_addc_u32 s57, s89, s79
	s_cmp_eq_u32 s9, s90
	s_cselect_b32 s78, s12, s56
	s_cselect_b32 s79, s13, s57
	s_cselect_b32 s56, s86, s64
	s_cselect_b32 s57, s87, s69
	s_add_u32 s90, s78, s0
	s_addc_u32 s91, s79, 0
	s_add_i32 s93, 0, 0x10000
	v_add_u32_e32 v0, s93, v174
	s_add_i32 s6, 0, 0x14000
	ds_read_b128 v[130:133], v0
	ds_read_b128 v[134:137], v0 offset:1024
	ds_read_b128 v[138:141], v0 offset:2048
	ds_read_b128 v[142:145], v0 offset:3072
	v_add_u32_e32 v0, s6, v174
	ds_read_b128 v[158:161], v0
	ds_read_b128 v[162:165], v0 offset:1024
	ds_read_b128 v[166:169], v0 offset:2048
	ds_read_b128 v[170:173], v0 offset:3072
	s_lshl_b64 s[14:15], s[14:15], s8
	s_add_u32 s14, s20, s14
	s_addc_u32 s15, s21, s15
	v_lshl_add_u64 v[192:193], s[14:15], 0, v[148:149]
	s_add_i32 m0, s55, 0xc000
	ds_read_b128 v[180:183], v147
	ds_read_b128 v[184:187], v147 offset:1024
	ds_read_b128 v[188:191], v147 offset:2048
	ds_read_b128 v[196:199], v147 offset:3072
	ds_read_b128 v[200:203], v147 offset:4096
	ds_read_b128 v[216:219], v147 offset:5120
	ds_read_b128 v[222:225], v147 offset:6144
	ds_read_b128 v[226:229], v147 offset:7168
	global_load_lds_dwordx4 v[192:193], off
	v_lshl_add_u64 v[192:193], s[14:15], 0, v[152:153]
	s_add_i32 m0, s55, 0xe000
	s_nop 0
	global_load_lds_dwordx4 v[192:193], off
	s_waitcnt vmcnt(8)
	s_waitcnt lgkmcnt(0)
	s_barrier
; #define S_STAGE(bufoff, gbase, voff) do { _Pragma("unroll") for (int _i = 0; _i < 2; ++_i) \
;     __builtin_amdgcn_global_load_lds((const unsigned*)((gbase) + (voff)[_i]), (LAS unsigned*)(lds + (bufoff) + ldsw + _i * 8192), 16, 0, 0); } while (0)
; #define S_LDA(dst, b, h) do { _Pragma("unroll") for (int m = 0; m < 4; ++m) _Pragma("unroll") for (int k = 0; k < 2; ++k) dst[m][k] = *(const LAS bf16x8*)(lds + S_SA(b, h) + aoff + m * 2048 + k * 1024); } while (0)
; #define S_MMA(ai, bj, At_, Bt_) do { __builtin_amdgcn_s_setprio(1); _Pragma("unroll") for (int m = 0; m < 4; ++m) _Pragma("unroll") for (int n = 0; n < 2; ++n) _Pragma("unroll") for (int k = 0; k < 2; ++k) \
;     acc[ai][bj][m][n] = __builtin_amdgcn_mfma_f32_16x16x32_bf16(Bt_[n][k], At_[m][k], acc[ai][bj][m][n], 0, 0, 0); __builtin_amdgcn_s_setprio(0); } while (0)
; #define S_WAIT_V(n) asm volatile("s_waitcnt vmcnt(" #n ")" ::: "memory")
; #define S_WAIT_L(n) asm volatile("s_waitcnt lgkmcnt(" #n ")" ::: "memory")
; #define S_BAR __builtin_amdgcn_s_barrier()
; #define S_SCHED __builtin_amdgcn_sched_barrier(0)
; DI void gemm_phase(LAS unsigned char* lds, const GemmDesc& d, float* __restrict__ X) {
;     ...
;       S_WAIT_V(8); S_WAIT_L(0); S_BAR; S_MMA(0, 0, At, B0); S_MMA(0, 1, At, B1); S_BAR; S_SCHED;
;       S_LDA(At, 0, 1); S_STAGE(S_SB(0, 0), b2, voffB); S_STAGE(S_SB(0, 1), b2 + hstepB, voffB); S_STAGE(S_SA(0, 0), a2, voffA);
;       S_WAIT_V(8); S_WAIT_L(0); S_BAR; S_MMA(1, 0, At, B0); S_MMA(1, 1, At, B1); S_BAR; S_SCHED;
	s_setprio 1
	s_waitcnt lgkmcnt(0)
	v_mfma_f32_16x16x32_bf16 v[126:129], v[130:133], v[180:183], v[126:129]
	v_mfma_f32_16x16x32_bf16 v[122:125], v[138:141], v[180:183], v[122:125]
	v_mfma_f32_16x16x32_bf16 v[110:113], v[130:133], v[188:191], v[110:113]
	v_mfma_f32_16x16x32_bf16 v[106:109], v[138:141], v[188:191], v[106:109]
	v_mfma_f32_16x16x32_bf16 v[94:97], v[130:133], v[200:203], v[94:97]
	v_mfma_f32_16x16x32_bf16 v[90:93], v[138:141], v[200:203], v[90:93]
	v_mfma_f32_16x16x32_bf16 v[78:81], v[130:133], v[222:225], v[78:81]
	v_mfma_f32_16x16x32_bf16 v[74:77], v[138:141], v[222:225], v[74:77]
	v_mfma_f32_16x16x32_bf16 v[126:129], v[134:137], v[184:187], v[126:129]
	v_mfma_f32_16x16x32_bf16 v[122:125], v[142:145], v[184:187], v[122:125]
	v_mfma_f32_16x16x32_bf16 v[110:113], v[134:137], v[196:199], v[110:113]
	v_mfma_f32_16x16x32_bf16 v[106:109], v[142:145], v[196:199], v[106:109]
	v_mfma_f32_16x16x32_bf16 v[94:97], v[134:137], v[216:219], v[94:97]
	v_mfma_f32_16x16x32_bf16 v[90:93], v[142:145], v[216:219], v[90:93]
	v_mfma_f32_16x16x32_bf16 v[78:81], v[134:137], v[226:229], v[78:81]
	v_mfma_f32_16x16x32_bf16 v[74:77], v[142:145], v[226:229], v[74:77]
	s_setprio 0
	s_setprio 1
	v_mfma_f32_16x16x32_bf16 v[118:121], v[158:161], v[180:183], v[118:121]
	v_mfma_f32_16x16x32_bf16 v[114:117], v[166:169], v[180:183], v[114:117]
	v_mfma_f32_16x16x32_bf16 v[102:105], v[158:161], v[188:191], v[102:105]
	v_mfma_f32_16x16x32_bf16 v[98:101], v[166:169], v[188:191], v[98:101]
	v_mfma_f32_16x16x32_bf16 v[86:89], v[158:161], v[200:203], v[86:89]
	v_mfma_f32_16x16x32_bf16 v[82:85], v[166:169], v[200:203], v[82:85]
	v_mfma_f32_16x16x32_bf16 v[70:73], v[158:161], v[222:225], v[70:73]
	v_mfma_f32_16x16x32_bf16 v[66:69], v[166:169], v[222:225], v[66:69]
	v_mfma_f32_16x16x32_bf16 v[118:121], v[162:165], v[184:187], v[118:121]
	v_mfma_f32_16x16x32_bf16 v[114:117], v[170:173], v[184:187], v[114:117]
	v_mfma_f32_16x16x32_bf16 v[102:105], v[162:165], v[196:199], v[102:105]
	v_mfma_f32_16x16x32_bf16 v[98:101], v[170:173], v[196:199], v[98:101]
	v_mfma_f32_16x16x32_bf16 v[86:89], v[162:165], v[216:219], v[86:89]
	v_mfma_f32_16x16x32_bf16 v[82:85], v[170:173], v[216:219], v[82:85]
	v_mfma_f32_16x16x32_bf16 v[70:73], v[162:165], v[226:229], v[70:73]
	v_mfma_f32_16x16x32_bf16 v[66:69], v[170:173], v[226:229], v[66:69]
	s_setprio 0
	s_barrier
	s_add_i32 s14, s93, s51
	v_lshl_add_u64 v[192:193], s[56:57], 0, v[150:151]
	s_mov_b32 m0, s14
	ds_read_b128 v[180:183], v147 offset:16384
	ds_read_b128 v[184:187], v147 offset:17408
	ds_read_b128 v[188:191], v147 offset:18432
	ds_read_b128 v[196:199], v147 offset:19456
	ds_read_b128 v[200:203], v147 offset:20480
	ds_read_b128 v[216:219], v147 offset:21504
	ds_read_b128 v[222:225], v147 offset:22528
	ds_read_b128 v[226:229], v147 offset:23552
	global_load_lds_dwordx4 v[192:193], off
	s_add_i32 m0, s14, 0x2000
	s_add_u32 s14, s56, s50
	v_lshl_add_u64 v[230:231], s[56:57], 0, v[154:155]
	s_addc_u32 s15, s57, 0
	s_add_i32 s6, s6, s51
	global_load_lds_dwordx4 v[230:231], off
	v_lshl_add_u64 v[232:233], s[14:15], 0, v[150:151]
	s_mov_b32 m0, s6
	v_lshl_add_u64 v[234:235], s[14:15], 0, v[154:155]
	global_load_lds_dwordx4 v[232:233], off
	s_add_i32 m0, s6, 0x2000
	v_lshl_add_u64 v[236:237], s[78:79], 0, v[148:149]
	global_load_lds_dwordx4 v[234:235], off
	s_mov_b32 m0, s55
	s_nop 0
	global_load_lds_dwordx4 v[236:237], off
	v_lshl_add_u64 v[236:237], s[78:79], 0, v[152:153]
	s_mov_b32 m0, s58
	s_nop 0
	global_load_lds_dwordx4 v[236:237], off
	s_waitcnt vmcnt(8)
	s_waitcnt lgkmcnt(0)
	s_barrier
	s_setprio 1
	s_waitcnt lgkmcnt(0)
	v_mfma_f32_16x16x32_bf16 v[62:65], v[130:133], v[180:183], v[62:65]
	v_mfma_f32_16x16x32_bf16 v[58:61], v[138:141], v[180:183], v[58:61]
	v_mfma_f32_16x16x32_bf16 v[46:49], v[130:133], v[188:191], v[46:49]
	v_mfma_f32_16x16x32_bf16 v[42:45], v[138:141], v[188:191], v[42:45]
	v_mfma_f32_16x16x32_bf16 v[30:33], v[130:133], v[200:203], v[30:33]
	v_mfma_f32_16x16x32_bf16 v[26:29], v[138:141], v[200:203], v[26:29]
	v_mfma_f32_16x16x32_bf16 v[14:17], v[130:133], v[222:225], v[14:17]
	v_mfma_f32_16x16x32_bf16 v[10:13], v[138:141], v[222:225], v[10:13]
	v_mfma_f32_16x16x32_bf16 v[62:65], v[134:137], v[184:187], v[62:65]
	v_mfma_f32_16x16x32_bf16 v[58:61], v[142:145], v[184:187], v[58:61]
	v_mfma_f32_16x16x32_bf16 v[46:49], v[134:137], v[196:199], v[46:49]
	v_mfma_f32_16x16x32_bf16 v[42:45], v[142:145], v[196:199], v[42:45]
	v_mfma_f32_16x16x32_bf16 v[30:33], v[134:137], v[216:219], v[30:33]
	v_mfma_f32_16x16x32_bf16 v[26:29], v[142:145], v[216:219], v[26:29]
	v_mfma_f32_16x16x32_bf16 v[14:17], v[134:137], v[226:229], v[14:17]
	v_mfma_f32_16x16x32_bf16 v[10:13], v[142:145], v[226:229], v[10:13]
	s_setprio 0
	s_setprio 1
	v_mfma_f32_16x16x32_bf16 v[54:57], v[158:161], v[180:183], v[54:57]
	v_mfma_f32_16x16x32_bf16 v[50:53], v[166:169], v[180:183], v[50:53]
	v_mfma_f32_16x16x32_bf16 v[38:41], v[158:161], v[188:191], v[38:41]
	v_mfma_f32_16x16x32_bf16 v[34:37], v[166:169], v[188:191], v[34:37]
	v_mfma_f32_16x16x32_bf16 v[22:25], v[158:161], v[200:203], v[22:25]
	v_mfma_f32_16x16x32_bf16 v[18:21], v[166:169], v[200:203], v[18:21]
	v_mfma_f32_16x16x32_bf16 v[6:9], v[158:161], v[222:225], v[6:9]
	v_mfma_f32_16x16x32_bf16 v[2:5], v[166:169], v[222:225], v[2:5]
	v_mfma_f32_16x16x32_bf16 v[54:57], v[162:165], v[184:187], v[54:57]
	v_mfma_f32_16x16x32_bf16 v[50:53], v[170:173], v[184:187], v[50:53]
	v_mfma_f32_16x16x32_bf16 v[38:41], v[162:165], v[196:199], v[38:41]
	v_mfma_f32_16x16x32_bf16 v[34:37], v[170:173], v[196:199], v[34:37]
	v_mfma_f32_16x16x32_bf16 v[22:25], v[162:165], v[216:219], v[22:25]
	v_mfma_f32_16x16x32_bf16 v[18:21], v[170:173], v[216:219], v[18:21]
	v_mfma_f32_16x16x32_bf16 v[6:9], v[162:165], v[226:229], v[6:9]
	v_mfma_f32_16x16x32_bf16 v[2:5], v[170:173], v[226:229], v[2:5]
	s_setprio 0
	s_barrier
; #define S_STAGE(bufoff, gbase, voff) do { _Pragma("unroll") for (int _i = 0; _i < 2; ++_i) \
;     __builtin_amdgcn_global_load_lds((const unsigned*)((gbase) + (voff)[_i]), (LAS unsigned*)(lds + (bufoff) + ldsw + _i * 8192), 16, 0, 0); } while (0)
; #define S_LDA(dst, b, h) do { _Pragma("unroll") for (int m = 0; m < 4; ++m) _Pragma("unroll") for (int k = 0; k < 2; ++k) dst[m][k] = *(const LAS bf16x8*)(lds + S_SA(b, h) + aoff + m * 2048 + k * 1024); } while (0)
; #define S_LDB(dst, b, h) do { _Pragma("unroll") for (int n = 0; n < 2; ++n) _Pragma("unroll") for (int k = 0; k < 2; ++k) dst[n][k] = *(const LAS bf16x8*)(lds + S_SB(b, h) + boff + n * 2048 + k * 1024); } while (0)
; #define S_MMA(ai, bj, At_, Bt_) do { __builtin_amdgcn_s_setprio(1); _Pragma("unroll") for (int m = 0; m < 4; ++m) _Pragma("unroll") for (int n = 0; n < 2; ++n) _Pragma("unroll") for (int k = 0; k < 2; ++k) \
;     acc[ai][bj][m][n] = __builtin_amdgcn_mfma_f32_16x16x32_bf16(Bt_[n][k], At_[m][k], acc[ai][bj][m][n], 0, 0, 0); __builtin_amdgcn_s_setprio(0); } while (0)
; #define S_WAIT_V(n) asm volatile("s_waitcnt vmcnt(" #n ")" ::: "memory")
; #define S_WAIT_L(n) asm volatile("s_waitcnt lgkmcnt(" #n ")" ::: "memory")
; #define S_BAR __builtin_amdgcn_s_barrier()
; #define S_SCHED __builtin_amdgcn_sched_barrier(0)
; DI void gemm_phase(LAS unsigned char* lds, const GemmDesc& d, float* __restrict__ X) {
;     ...
;       S_LDB(B0, 1, 0); S_LDB(B1, 1, 1); S_SCHED; S_LDA(At, 1, 0); S_STAGE(S_SA(0, 1), a2 + hstepA, voffA);
;       S_WAIT_V(8); S_WAIT_L(0); S_BAR; S_MMA(0, 0, At, B0); S_MMA(0, 1, At, B1); S_BAR; S_SCHED;
;       S_LDA(At, 1, 1); S_STAGE(S_SB(1, 0), b3, voffB); S_STAGE(S_SB(1, 1), b3 + hstepB, voffB); S_STAGE(S_SA(1, 0), a3, voffA);
;       S_WAIT_V(8); S_WAIT_L(0); S_BAR; S_MMA(1, 0, At, B0); S_MMA(1, 1, At, B1); S_BAR; S_SCHED;
	s_add_i32 s6, 0, 0x18000
	v_add_u32_e32 v0, s6, v174
	s_add_i32 s56, 0, 0x1c000
	ds_read_b128 v[130:133], v0
	ds_read_b128 v[134:137], v0 offset:1024
	ds_read_b128 v[138:141], v0 offset:2048
	ds_read_b128 v[142:145], v0 offset:3072
	v_add_u32_e32 v0, s56, v174
	ds_read_b128 v[158:161], v0
	ds_read_b128 v[162:165], v0 offset:1024
	ds_read_b128 v[166:169], v0 offset:2048
	ds_read_b128 v[170:173], v0 offset:3072
	s_add_u32 s14, s78, s27
	s_addc_u32 s15, s79, 0
	s_mov_b32 m0, s59
	v_lshl_add_u64 v[236:237], s[14:15], 0, v[148:149]
	ds_read_b128 v[180:183], v147 offset:32768
	ds_read_b128 v[184:187], v147 offset:33792
	ds_read_b128 v[188:191], v147 offset:34816
	ds_read_b128 v[196:199], v147 offset:35840
	ds_read_b128 v[200:203], v147 offset:36864
	ds_read_b128 v[216:219], v147 offset:37888
	ds_read_b128 v[222:225], v147 offset:38912
	ds_read_b128 v[226:229], v147 offset:39936
	global_load_lds_dwordx4 v[236:237], off
	v_lshl_add_u64 v[236:237], s[14:15], 0, v[152:153]
	s_mov_b32 m0, s83
	s_nop 0
	global_load_lds_dwordx4 v[236:237], off
	s_waitcnt vmcnt(8)
	s_waitcnt lgkmcnt(0)
	s_barrier
	s_setprio 1
	s_waitcnt lgkmcnt(0)
	v_mfma_f32_16x16x32_bf16 v[126:129], v[130:133], v[180:183], v[126:129]
	v_mfma_f32_16x16x32_bf16 v[122:125], v[138:141], v[180:183], v[122:125]
	v_mfma_f32_16x16x32_bf16 v[110:113], v[130:133], v[188:191], v[110:113]
	v_mfma_f32_16x16x32_bf16 v[106:109], v[138:141], v[188:191], v[106:109]
	v_mfma_f32_16x16x32_bf16 v[94:97], v[130:133], v[200:203], v[94:97]
	v_mfma_f32_16x16x32_bf16 v[90:93], v[138:141], v[200:203], v[90:93]
	v_mfma_f32_16x16x32_bf16 v[78:81], v[130:133], v[222:225], v[78:81]
	v_mfma_f32_16x16x32_bf16 v[74:77], v[138:141], v[222:225], v[74:77]
	v_mfma_f32_16x16x32_bf16 v[126:129], v[134:137], v[184:187], v[126:129]
	v_mfma_f32_16x16x32_bf16 v[122:125], v[142:145], v[184:187], v[122:125]
	v_mfma_f32_16x16x32_bf16 v[110:113], v[134:137], v[196:199], v[110:113]
	v_mfma_f32_16x16x32_bf16 v[106:109], v[142:145], v[196:199], v[106:109]
	v_mfma_f32_16x16x32_bf16 v[94:97], v[134:137], v[216:219], v[94:97]
	v_mfma_f32_16x16x32_bf16 v[90:93], v[142:145], v[216:219], v[90:93]
	v_mfma_f32_16x16x32_bf16 v[78:81], v[134:137], v[226:229], v[78:81]
	v_mfma_f32_16x16x32_bf16 v[74:77], v[142:145], v[226:229], v[74:77]
	s_setprio 0
	s_setprio 1
	v_mfma_f32_16x16x32_bf16 v[118:121], v[158:161], v[180:183], v[118:121]
	v_mfma_f32_16x16x32_bf16 v[114:117], v[166:169], v[180:183], v[114:117]
	v_mfma_f32_16x16x32_bf16 v[102:105], v[158:161], v[188:191], v[102:105]
	v_mfma_f32_16x16x32_bf16 v[98:101], v[166:169], v[188:191], v[98:101]
	v_mfma_f32_16x16x32_bf16 v[86:89], v[158:161], v[200:203], v[86:89]
	v_mfma_f32_16x16x32_bf16 v[82:85], v[166:169], v[200:203], v[82:85]
	v_mfma_f32_16x16x32_bf16 v[70:73], v[158:161], v[222:225], v[70:73]
	v_mfma_f32_16x16x32_bf16 v[66:69], v[166:169], v[222:225], v[66:69]
	v_mfma_f32_16x16x32_bf16 v[118:121], v[162:165], v[184:187], v[118:121]
	v_mfma_f32_16x16x32_bf16 v[114:117], v[170:173], v[184:187], v[114:117]
	v_mfma_f32_16x16x32_bf16 v[102:105], v[162:165], v[196:199], v[102:105]
	v_mfma_f32_16x16x32_bf16 v[98:101], v[170:173], v[196:199], v[98:101]
	v_mfma_f32_16x16x32_bf16 v[86:89], v[162:165], v[216:219], v[86:89]
	v_mfma_f32_16x16x32_bf16 v[82:85], v[170:173], v[216:219], v[82:85]
	v_mfma_f32_16x16x32_bf16 v[70:73], v[162:165], v[226:229], v[70:73]
	v_mfma_f32_16x16x32_bf16 v[66:69], v[170:173], v[226:229], v[66:69]
	s_setprio 0
	s_barrier
	s_add_i32 s6, s6, s51
	v_lshl_add_u64 v[192:193], v[192:193], 0, s[98:99]
	s_mov_b32 m0, s6
	ds_read_b128 v[180:183], v147 offset:49152
	ds_read_b128 v[184:187], v147 offset:50176
	ds_read_b128 v[188:191], v147 offset:51200
	ds_read_b128 v[196:199], v147 offset:52224
	ds_read_b128 v[200:203], v147 offset:53248
	ds_read_b128 v[216:219], v147 offset:54272
	ds_read_b128 v[222:225], v147 offset:55296
	ds_read_b128 v[226:229], v147 offset:56320
	global_load_lds_dwordx4 v[192:193], off
	v_lshl_add_u64 v[192:193], v[230:231], 0, s[98:99]
	s_add_i32 m0, s6, 0x2000
	s_add_i32 s6, s56, s51
	global_load_lds_dwordx4 v[192:193], off
	v_lshl_add_u64 v[192:193], v[232:233], 0, s[98:99]
	s_mov_b32 m0, s6
	s_nop 0
	global_load_lds_dwordx4 v[192:193], off
	v_lshl_add_u64 v[192:193], v[234:235], 0, s[98:99]
	s_add_i32 m0, s6, 0x2000
	s_nop 0
	global_load_lds_dwordx4 v[192:193], off
	v_lshl_add_u64 v[192:193], s[90:91], 0, v[148:149]
	s_mov_b32 m0, s82
	s_nop 0
	global_load_lds_dwordx4 v[192:193], off
	v_lshl_add_u64 v[192:193], s[90:91], 0, v[152:153]
	s_mov_b32 m0, s94
	s_nop 0
	global_load_lds_dwordx4 v[192:193], off
	s_waitcnt vmcnt(8)
	s_waitcnt lgkmcnt(0)
	s_barrier
; #define S_STAGE(bufoff, gbase, voff) do { _Pragma("unroll") for (int _i = 0; _i < 2; ++_i) \
;     __builtin_amdgcn_global_load_lds((const unsigned*)((gbase) + (voff)[_i]), (LAS unsigned*)(lds + (bufoff) + ldsw + _i * 8192), 16, 0, 0); } while (0)
; #define S_LDA(dst, b, h) do { _Pragma("unroll") for (int m = 0; m < 4; ++m) _Pragma("unroll") for (int k = 0; k < 2; ++k) dst[m][k] = *(const LAS bf16x8*)(lds + S_SA(b, h) + aoff + m * 2048 + k * 1024); } while (0)
; #define S_LDB(dst, b, h) do { _Pragma("unroll") for (int n = 0; n < 2; ++n) _Pragma("unroll") for (int k = 0; k < 2; ++k) dst[n][k] = *(const LAS bf16x8*)(lds + S_SB(b, h) + boff + n * 2048 + k * 1024); } while (0)
; #define S_MMA(ai, bj, At_, Bt_) do { __builtin_amdgcn_s_setprio(1); _Pragma("unroll") for (int m = 0; m < 4; ++m) _Pragma("unroll") for (int n = 0; n < 2; ++n) _Pragma("unroll") for (int k = 0; k < 2; ++k) \
;     acc[ai][bj][m][n] = __builtin_amdgcn_mfma_f32_16x16x32_bf16(Bt_[n][k], At_[m][k], acc[ai][bj][m][n], 0, 0, 0); __builtin_amdgcn_s_setprio(0); } while (0)
; #define S_WAIT_V(n) asm volatile("s_waitcnt vmcnt(" #n ")" ::: "memory")
; #define S_WAIT_L(n) asm volatile("s_waitcnt lgkmcnt(" #n ")" ::: "memory")
; #define S_BAR __builtin_amdgcn_s_barrier()
; #define S_SCHED __builtin_amdgcn_sched_barrier(0)
; DI void gemm_phase(LAS unsigned char* lds, const GemmDesc& d, float* __restrict__ X) {
;     ...
;     for (int t = 0; t < nt; t += 2) {
;       const bool last = (t == nt - 2);
;       const char* a1 = cA + (size_t)(t + 1) * kstepA;
;       const char* a2 = last ? nA : cA + (size_t)(t + 2) * kstepA; const char* b2 = last ? nB : cB + (size_t)(t + 2) * kstepB;
;       const char* a3 = a2 + kstepA; const char* b3 = b2 + kstepB;
;       S_LDB(B0, 0, 0); S_LDB(B1, 0, 1); S_SCHED; S_LDA(At, 0, 0); S_STAGE(S_SA(1, 1), a1 + hstepA, voffA);
;       S_WAIT_V(8); S_WAIT_L(0); S_BAR; S_MMA(0, 0, At, B0); S_MMA(0, 1, At, B1); S_BAR; S_SCHED;
;     ...
;       S_WAIT_V(8); S_WAIT_L(0); S_BAR; S_MMA(1, 0, At, B0); S_MMA(1, 1, At, B1); S_BAR; S_SCHED;
;     }
	s_setprio 1
	s_waitcnt lgkmcnt(0)
	v_mfma_f32_16x16x32_bf16 v[62:65], v[130:133], v[180:183], v[62:65]
	v_mfma_f32_16x16x32_bf16 v[58:61], v[138:141], v[180:183], v[58:61]
	v_mfma_f32_16x16x32_bf16 v[46:49], v[130:133], v[188:191], v[46:49]
	v_mfma_f32_16x16x32_bf16 v[42:45], v[138:141], v[188:191], v[42:45]
	v_mfma_f32_16x16x32_bf16 v[30:33], v[130:133], v[200:203], v[30:33]
	v_mfma_f32_16x16x32_bf16 v[26:29], v[138:141], v[200:203], v[26:29]
	v_mfma_f32_16x16x32_bf16 v[14:17], v[130:133], v[222:225], v[14:17]
	v_mfma_f32_16x16x32_bf16 v[10:13], v[138:141], v[222:225], v[10:13]
	v_mfma_f32_16x16x32_bf16 v[62:65], v[134:137], v[184:187], v[62:65]
	v_mfma_f32_16x16x32_bf16 v[58:61], v[142:145], v[184:187], v[58:61]
	v_mfma_f32_16x16x32_bf16 v[46:49], v[134:137], v[196:199], v[46:49]
	v_mfma_f32_16x16x32_bf16 v[42:45], v[142:145], v[196:199], v[42:45]
	v_mfma_f32_16x16x32_bf16 v[30:33], v[134:137], v[216:219], v[30:33]
	v_mfma_f32_16x16x32_bf16 v[26:29], v[142:145], v[216:219], v[26:29]
	v_mfma_f32_16x16x32_bf16 v[14:17], v[134:137], v[226:229], v[14:17]
	v_mfma_f32_16x16x32_bf16 v[10:13], v[142:145], v[226:229], v[10:13]
	s_setprio 0
	s_setprio 1
	v_mfma_f32_16x16x32_bf16 v[54:57], v[158:161], v[180:183], v[54:57]
	v_mfma_f32_16x16x32_bf16 v[50:53], v[166:169], v[180:183], v[50:53]
	v_mfma_f32_16x16x32_bf16 v[38:41], v[158:161], v[188:191], v[38:41]
	v_mfma_f32_16x16x32_bf16 v[34:37], v[166:169], v[188:191], v[34:37]
	v_mfma_f32_16x16x32_bf16 v[22:25], v[158:161], v[200:203], v[22:25]
	v_mfma_f32_16x16x32_bf16 v[18:21], v[166:169], v[200:203], v[18:21]
	v_mfma_f32_16x16x32_bf16 v[6:9], v[158:161], v[222:225], v[6:9]
	v_mfma_f32_16x16x32_bf16 v[2:5], v[166:169], v[222:225], v[2:5]
	v_mfma_f32_16x16x32_bf16 v[54:57], v[162:165], v[184:187], v[54:57]
	v_mfma_f32_16x16x32_bf16 v[50:53], v[170:173], v[184:187], v[50:53]
	v_mfma_f32_16x16x32_bf16 v[38:41], v[162:165], v[196:199], v[38:41]
	v_mfma_f32_16x16x32_bf16 v[34:37], v[170:173], v[196:199], v[34:37]
	v_mfma_f32_16x16x32_bf16 v[22:25], v[162:165], v[216:219], v[22:25]
	v_mfma_f32_16x16x32_bf16 v[18:21], v[170:173], v[216:219], v[18:21]
	v_mfma_f32_16x16x32_bf16 v[6:9], v[162:165], v[226:229], v[6:9]
	v_mfma_f32_16x16x32_bf16 v[2:5], v[170:173], v[226:229], v[2:5]
	s_setprio 0
	s_barrier
	s_add_u32 s64, s64, 0x100
	s_addc_u32 s69, s69, 0
	s_cmp_ge_u32 vcc_lo, s1
	s_mov_b64 s[90:91], vcc
	s_cbranch_scc0 .LBB0_346
	s_branch .Lgemm_join
.Lgemm_h1:
	s_add_u32 s14, s90, 1
	s_addc_u32 s15, s91, 0
	s_add_u32 vcc_lo, s90, 2
	s_addc_u32 vcc_hi, s91, 0
	s_lshl_b64 s[78:79], vcc, s8
	s_add_u32 s56, s88, s78
	s_addc_u32 s57, s89, s79
	s_cmp_eq_u32 s9, s90
	s_cselect_b32 s78, s12, s56
	s_cselect_b32 s79, s13, s57
	s_cselect_b32 s56, s86, s64
	s_cselect_b32 s57, s87, s69
	s_add_u32 s90, s78, s0
	s_addc_u32 s91, s79, 0
	s_add_i32 s93, 0, 0x10000
	v_add_u32_e32 v0, s93, v174
	s_add_i32 s6, 0, 0x14000
	ds_read_b128 v[130:133], v0
	ds_read_b128 v[134:137], v0 offset:1024
	ds_read_b128 v[138:141], v0 offset:2048
	ds_read_b128 v[142:145], v0 offset:3072
	v_add_u32_e32 v0, s6, v174
	ds_read_b128 v[158:161], v0
	ds_read_b128 v[162:165], v0 offset:1024
	ds_read_b128 v[166:169], v0 offset:2048
	ds_read_b128 v[170:173], v0 offset:3072
	s_lshl_b64 s[14:15], s[14:15], s8
	s_add_u32 s14, s20, s14
	s_addc_u32 s15, s21, s15
	v_lshl_add_u64 v[192:193], s[14:15], 0, v[148:149]
	s_add_i32 m0, s55, 0xc000
	ds_read_b128 v[180:183], v147
	ds_read_b128 v[184:187], v147 offset:1024
	ds_read_b128 v[188:191], v147 offset:2048
	ds_read_b128 v[196:199], v147 offset:3072
	ds_read_b128 v[200:203], v147 offset:4096
	ds_read_b128 v[216:219], v147 offset:5120
	ds_read_b128 v[222:225], v147 offset:6144
	ds_read_b128 v[226:229], v147 offset:7168
	global_load_lds_dwordx4 v[192:193], off
	v_lshl_add_u64 v[192:193], s[14:15], 0, v[152:153]
	s_add_i32 m0, s55, 0xe000
	s_nop 0
	global_load_lds_dwordx4 v[192:193], off
	s_waitcnt vmcnt(8)
	s_waitcnt lgkmcnt(0)
	s_barrier
	s_setprio 1
	s_waitcnt lgkmcnt(0)
	v_mfma_f32_16x16x32_bf16 v[126:129], v[130:133], v[180:183], v[126:129]
	v_mfma_f32_16x16x32_bf16 v[122:125], v[138:141], v[180:183], v[122:125]
	v_mfma_f32_16x16x32_bf16 v[110:113], v[130:133], v[188:191], v[110:113]
	v_mfma_f32_16x16x32_bf16 v[106:109], v[138:141], v[188:191], v[106:109]
	v_mfma_f32_16x16x32_bf16 v[94:97], v[130:133], v[200:203], v[94:97]
	v_mfma_f32_16x16x32_bf16 v[90:93], v[138:141], v[200:203], v[90:93]
	v_mfma_f32_16x16x32_bf16 v[78:81], v[130:133], v[222:225], v[78:81]
	v_mfma_f32_16x16x32_bf16 v[74:77], v[138:141], v[222:225], v[74:77]
	v_mfma_f32_16x16x32_bf16 v[126:129], v[134:137], v[184:187], v[126:129]
	v_mfma_f32_16x16x32_bf16 v[122:125], v[142:145], v[184:187], v[122:125]
	v_mfma_f32_16x16x32_bf16 v[110:113], v[134:137], v[196:199], v[110:113]
	v_mfma_f32_16x16x32_bf16 v[106:109], v[142:145], v[196:199], v[106:109]
	v_mfma_f32_16x16x32_bf16 v[94:97], v[134:137], v[216:219], v[94:97]
	v_mfma_f32_16x16x32_bf16 v[90:93], v[142:145], v[216:219], v[90:93]
	v_mfma_f32_16x16x32_bf16 v[78:81], v[134:137], v[226:229], v[78:81]
	v_mfma_f32_16x16x32_bf16 v[74:77], v[142:145], v[226:229], v[74:77]
	s_setprio 1
	s_setprio 1
	v_mfma_f32_16x16x32_bf16 v[118:121], v[158:161], v[180:183], v[118:121]
	v_mfma_f32_16x16x32_bf16 v[114:117], v[166:169], v[180:183], v[114:117]
	v_mfma_f32_16x16x32_bf16 v[102:105], v[158:161], v[188:191], v[102:105]
	v_mfma_f32_16x16x32_bf16 v[98:101], v[166:169], v[188:191], v[98:101]
	v_mfma_f32_16x16x32_bf16 v[86:89], v[158:161], v[200:203], v[86:89]
	v_mfma_f32_16x16x32_bf16 v[82:85], v[166:169], v[200:203], v[82:85]
	v_mfma_f32_16x16x32_bf16 v[70:73], v[158:161], v[222:225], v[70:73]
	v_mfma_f32_16x16x32_bf16 v[66:69], v[166:169], v[222:225], v[66:69]
	v_mfma_f32_16x16x32_bf16 v[118:121], v[162:165], v[184:187], v[118:121]
	v_mfma_f32_16x16x32_bf16 v[114:117], v[170:173], v[184:187], v[114:117]
	v_mfma_f32_16x16x32_bf16 v[102:105], v[162:165], v[196:199], v[102:105]
	v_mfma_f32_16x16x32_bf16 v[98:101], v[170:173], v[196:199], v[98:101]
	v_mfma_f32_16x16x32_bf16 v[86:89], v[162:165], v[216:219], v[86:89]
	v_mfma_f32_16x16x32_bf16 v[82:85], v[170:173], v[216:219], v[82:85]
	v_mfma_f32_16x16x32_bf16 v[70:73], v[162:165], v[226:229], v[70:73]
	v_mfma_f32_16x16x32_bf16 v[66:69], v[170:173], v[226:229], v[66:69]
	s_setprio 1
	s_barrier
; #define S_STAGE(bufoff, gbase, voff) do { _Pragma("unroll") for (int _i = 0; _i < 2; ++_i) \
;     __builtin_amdgcn_global_load_lds((const unsigned*)((gbase) + (voff)[_i]), (LAS unsigned*)(lds + (bufoff) + ldsw + _i * 8192), 16, 0, 0); } while (0)
; #define S_LDA(dst, b, h) do { _Pragma("unroll") for (int m = 0; m < 4; ++m) _Pragma("unroll") for (int k = 0; k < 2; ++k) dst[m][k] = *(const LAS bf16x8*)(lds + S_SA(b, h) + aoff + m * 2048 + k * 1024); } while (0)
; #define S_LDB(dst, b, h) do { _Pragma("unroll") for (int n = 0; n < 2; ++n) _Pragma("unroll") for (int k = 0; k < 2; ++k) dst[n][k] = *(const LAS bf16x8*)(lds + S_SB(b, h) + boff + n * 2048 + k * 1024); } while (0)
; #define S_MMA(ai, bj, At_, Bt_) do { __builtin_amdgcn_s_setprio(1); _Pragma("unroll") for (int m = 0; m < 4; ++m) _Pragma("unroll") for (int n = 0; n < 2; ++n) _Pragma("unroll") for (int k = 0; k < 2; ++k) \
;     acc[ai][bj][m][n] = __builtin_amdgcn_mfma_f32_16x16x32_bf16(Bt_[n][k], At_[m][k], acc[ai][bj][m][n], 0, 0, 0); __builtin_amdgcn_s_setprio(0); } while (0)
; #define S_WAIT_V(n) asm volatile("s_waitcnt vmcnt(" #n ")" ::: "memory")
; #define S_WAIT_L(n) asm volatile("s_waitcnt lgkmcnt(" #n ")" ::: "memory")
; #define S_BAR __builtin_amdgcn_s_barrier()
; #define S_SCHED __builtin_amdgcn_sched_barrier(0)
; DI void gemm_phase(LAS unsigned char* lds, const GemmDesc& d, float* __restrict__ X) {
;     ...
;       S_LDA(At, 0, 1); S_STAGE(S_SB(0, 0), b2, voffB); S_STAGE(S_SB(0, 1), b2 + hstepB, voffB); S_STAGE(S_SA(0, 0), a2, voffA);
;       S_WAIT_V(8); S_WAIT_L(0); S_BAR; S_MMA(1, 0, At, B0); S_MMA(1, 1, At, B1); S_BAR; S_SCHED;
;       S_LDB(B0, 1, 0); S_LDB(B1, 1, 1); S_SCHED; S_LDA(At, 1, 0); S_STAGE(S_SA(0, 1), a2 + hstepA, voffA);
;       S_WAIT_V(8); S_WAIT_L(0); S_BAR; S_MMA(0, 0, At, B0); S_MMA(0, 1, At, B1); S_BAR; S_SCHED;
	s_add_i32 s14, s93, s51
	v_lshl_add_u64 v[192:193], s[56:57], 0, v[150:151]
	s_mov_b32 m0, s14
	ds_read_b128 v[180:183], v147 offset:16384
	ds_read_b128 v[184:187], v147 offset:17408
	ds_read_b128 v[188:191], v147 offset:18432
	ds_read_b128 v[196:199], v147 offset:19456
	ds_read_b128 v[200:203], v147 offset:20480
	ds_read_b128 v[216:219], v147 offset:21504
	ds_read_b128 v[222:225], v147 offset:22528
	ds_read_b128 v[226:229], v147 offset:23552
	global_load_lds_dwordx4 v[192:193], off
	s_add_i32 m0, s14, 0x2000
	s_add_u32 s14, s56, s50
	v_lshl_add_u64 v[230:231], s[56:57], 0, v[154:155]
	s_addc_u32 s15, s57, 0
	s_add_i32 s6, s6, s51
	global_load_lds_dwordx4 v[230:231], off
	v_lshl_add_u64 v[232:233], s[14:15], 0, v[150:151]
	s_mov_b32 m0, s6
	v_lshl_add_u64 v[234:235], s[14:15], 0, v[154:155]
	global_load_lds_dwordx4 v[232:233], off
	s_add_i32 m0, s6, 0x2000
	v_lshl_add_u64 v[236:237], s[78:79], 0, v[148:149]
	global_load_lds_dwordx4 v[234:235], off
	s_mov_b32 m0, s55
	s_nop 0
	global_load_lds_dwordx4 v[236:237], off
	v_lshl_add_u64 v[236:237], s[78:79], 0, v[152:153]
	s_mov_b32 m0, s58
	s_nop 0
	global_load_lds_dwordx4 v[236:237], off
	s_waitcnt vmcnt(8)
	s_waitcnt lgkmcnt(0)
	s_barrier
	s_setprio 1
	s_waitcnt lgkmcnt(0)
	v_mfma_f32_16x16x32_bf16 v[62:65], v[130:133], v[180:183], v[62:65]
	v_mfma_f32_16x16x32_bf16 v[58:61], v[138:141], v[180:183], v[58:61]
	v_mfma_f32_16x16x32_bf16 v[46:49], v[130:133], v[188:191], v[46:49]
	v_mfma_f32_16x16x32_bf16 v[42:45], v[138:141], v[188:191], v[42:45]
	v_mfma_f32_16x16x32_bf16 v[30:33], v[130:133], v[200:203], v[30:33]
	v_mfma_f32_16x16x32_bf16 v[26:29], v[138:141], v[200:203], v[26:29]
	v_mfma_f32_16x16x32_bf16 v[14:17], v[130:133], v[222:225], v[14:17]
	v_mfma_f32_16x16x32_bf16 v[10:13], v[138:141], v[222:225], v[10:13]
	v_mfma_f32_16x16x32_bf16 v[62:65], v[134:137], v[184:187], v[62:65]
	v_mfma_f32_16x16x32_bf16 v[58:61], v[142:145], v[184:187], v[58:61]
	v_mfma_f32_16x16x32_bf16 v[46:49], v[134:137], v[196:199], v[46:49]
	v_mfma_f32_16x16x32_bf16 v[42:45], v[142:145], v[196:199], v[42:45]
	v_mfma_f32_16x16x32_bf16 v[30:33], v[134:137], v[216:219], v[30:33]
	v_mfma_f32_16x16x32_bf16 v[26:29], v[142:145], v[216:219], v[26:29]
	v_mfma_f32_16x16x32_bf16 v[14:17], v[134:137], v[226:229], v[14:17]
	v_mfma_f32_16x16x32_bf16 v[10:13], v[142:145], v[226:229], v[10:13]
	s_setprio 1
	s_setprio 1
	v_mfma_f32_16x16x32_bf16 v[54:57], v[158:161], v[180:183], v[54:57]
	v_mfma_f32_16x16x32_bf16 v[50:53], v[166:169], v[180:183], v[50:53]
	v_mfma_f32_16x16x32_bf16 v[38:41], v[158:161], v[188:191], v[38:41]
	v_mfma_f32_16x16x32_bf16 v[34:37], v[166:169], v[188:191], v[34:37]
	v_mfma_f32_16x16x32_bf16 v[22:25], v[158:161], v[200:203], v[22:25]
	v_mfma_f32_16x16x32_bf16 v[18:21], v[166:169], v[200:203], v[18:21]
	v_mfma_f32_16x16x32_bf16 v[6:9], v[158:161], v[222:225], v[6:9]
	v_mfma_f32_16x16x32_bf16 v[2:5], v[166:169], v[222:225], v[2:5]
	v_mfma_f32_16x16x32_bf16 v[54:57], v[162:165], v[184:187], v[54:57]
	v_mfma_f32_16x16x32_bf16 v[50:53], v[170:173], v[184:187], v[50:53]
	v_mfma_f32_16x16x32_bf16 v[38:41], v[162:165], v[196:199], v[38:41]
	v_mfma_f32_16x16x32_bf16 v[34:37], v[170:173], v[196:199], v[34:37]
	v_mfma_f32_16x16x32_bf16 v[22:25], v[162:165], v[216:219], v[22:25]
	v_mfma_f32_16x16x32_bf16 v[18:21], v[170:173], v[216:219], v[18:21]
	v_mfma_f32_16x16x32_bf16 v[6:9], v[162:165], v[226:229], v[6:9]
	v_mfma_f32_16x16x32_bf16 v[2:5], v[170:173], v[226:229], v[2:5]
	s_setprio 1
	s_barrier
	s_add_i32 s6, 0, 0x18000
	v_add_u32_e32 v0, s6, v174
	s_add_i32 s56, 0, 0x1c000
	ds_read_b128 v[130:133], v0
	ds_read_b128 v[134:137], v0 offset:1024
	ds_read_b128 v[138:141], v0 offset:2048
	ds_read_b128 v[142:145], v0 offset:3072
	v_add_u32_e32 v0, s56, v174
	ds_read_b128 v[158:161], v0
	ds_read_b128 v[162:165], v0 offset:1024
	ds_read_b128 v[166:169], v0 offset:2048
	ds_read_b128 v[170:173], v0 offset:3072
	s_add_u32 s14, s78, s27
	s_addc_u32 s15, s79, 0
	s_mov_b32 m0, s59
	v_lshl_add_u64 v[236:237], s[14:15], 0, v[148:149]
	ds_read_b128 v[180:183], v147 offset:32768
	ds_read_b128 v[184:187], v147 offset:33792
	ds_read_b128 v[188:191], v147 offset:34816
	ds_read_b128 v[196:199], v147 offset:35840
	ds_read_b128 v[200:203], v147 offset:36864
	ds_read_b128 v[216:219], v147 offset:37888
	ds_read_b128 v[222:225], v147 offset:38912
	ds_read_b128 v[226:229], v147 offset:39936
	global_load_lds_dwordx4 v[236:237], off
	v_lshl_add_u64 v[236:237], s[14:15], 0, v[152:153]
	s_mov_b32 m0, s83
	s_nop 0
	global_load_lds_dwordx4 v[236:237], off
	s_waitcnt vmcnt(8)
	s_waitcnt lgkmcnt(0)
	s_barrier
; #define S_STAGE(bufoff, gbase, voff) do { _Pragma("unroll") for (int _i = 0; _i < 2; ++_i) \
;     __builtin_amdgcn_global_load_lds((const unsigned*)((gbase) + (voff)[_i]), (LAS unsigned*)(lds + (bufoff) + ldsw + _i * 8192), 16, 0, 0); } while (0)
; #define S_LDA(dst, b, h) do { _Pragma("unroll") for (int m = 0; m < 4; ++m) _Pragma("unroll") for (int k = 0; k < 2; ++k) dst[m][k] = *(const LAS bf16x8*)(lds + S_SA(b, h) + aoff + m * 2048 + k * 1024); } while (0)
; #define S_LDB(dst, b, h) do { _Pragma("unroll") for (int n = 0; n < 2; ++n) _Pragma("unroll") for (int k = 0; k < 2; ++k) dst[n][k] = *(const LAS bf16x8*)(lds + S_SB(b, h) + boff + n * 2048 + k * 1024); } while (0)
; #define S_MMA(ai, bj, At_, Bt_) do { __builtin_amdgcn_s_setprio(1); _Pragma("unroll") for (int m = 0; m < 4; ++m) _Pragma("unroll") for (int n = 0; n < 2; ++n) _Pragma("unroll") for (int k = 0; k < 2; ++k) \
;     acc[ai][bj][m][n] = __builtin_amdgcn_mfma_f32_16x16x32_bf16(Bt_[n][k], At_[m][k], acc[ai][bj][m][n], 0, 0, 0); __builtin_amdgcn_s_setprio(0); } while (0)
; #define S_WAIT_V(n) asm volatile("s_waitcnt vmcnt(" #n ")" ::: "memory")
; #define S_WAIT_L(n) asm volatile("s_waitcnt lgkmcnt(" #n ")" ::: "memory")
; #define S_BAR __builtin_amdgcn_s_barrier()
; #define S_SCHED __builtin_amdgcn_sched_barrier(0)
; DI void gemm_phase(LAS unsigned char* lds, const GemmDesc& d, float* __restrict__ X) {
;     ...
;       S_LDB(B0, 1, 0); S_LDB(B1, 1, 1); S_SCHED; S_LDA(At, 1, 0); S_STAGE(S_SA(0, 1), a2 + hstepA, voffA);
;       S_WAIT_V(8); S_WAIT_L(0); S_BAR; S_MMA(0, 0, At, B0); S_MMA(0, 1, At, B1); S_BAR; S_SCHED;
;       S_LDA(At, 1, 1); S_STAGE(S_SB(1, 0), b3, voffB); S_STAGE(S_SB(1, 1), b3 + hstepB, voffB); S_STAGE(S_SA(1, 0), a3, voffA);
;       S_WAIT_V(8); S_WAIT_L(0); S_BAR; S_MMA(1, 0, At, B0); S_MMA(1, 1, At, B1); S_BAR; S_SCHED;
;     }
	s_setprio 1
	s_waitcnt lgkmcnt(0)
	v_mfma_f32_16x16x32_bf16 v[126:129], v[130:133], v[180:183], v[126:129]
	v_mfma_f32_16x16x32_bf16 v[122:125], v[138:141], v[180:183], v[122:125]
	v_mfma_f32_16x16x32_bf16 v[110:113], v[130:133], v[188:191], v[110:113]
	v_mfma_f32_16x16x32_bf16 v[106:109], v[138:141], v[188:191], v[106:109]
	v_mfma_f32_16x16x32_bf16 v[94:97], v[130:133], v[200:203], v[94:97]
	v_mfma_f32_16x16x32_bf16 v[90:93], v[138:141], v[200:203], v[90:93]
	v_mfma_f32_16x16x32_bf16 v[78:81], v[130:133], v[222:225], v[78:81]
	v_mfma_f32_16x16x32_bf16 v[74:77], v[138:141], v[222:225], v[74:77]
	v_mfma_f32_16x16x32_bf16 v[126:129], v[134:137], v[184:187], v[126:129]
	v_mfma_f32_16x16x32_bf16 v[122:125], v[142:145], v[184:187], v[122:125]
	v_mfma_f32_16x16x32_bf16 v[110:113], v[134:137], v[196:199], v[110:113]
	v_mfma_f32_16x16x32_bf16 v[106:109], v[142:145], v[196:199], v[106:109]
	v_mfma_f32_16x16x32_bf16 v[94:97], v[134:137], v[216:219], v[94:97]
	v_mfma_f32_16x16x32_bf16 v[90:93], v[142:145], v[216:219], v[90:93]
	v_mfma_f32_16x16x32_bf16 v[78:81], v[134:137], v[226:229], v[78:81]
	v_mfma_f32_16x16x32_bf16 v[74:77], v[142:145], v[226:229], v[74:77]
	s_setprio 1
	s_setprio 1
	v_mfma_f32_16x16x32_bf16 v[118:121], v[158:161], v[180:183], v[118:121]
	v_mfma_f32_16x16x32_bf16 v[114:117], v[166:169], v[180:183], v[114:117]
	v_mfma_f32_16x16x32_bf16 v[102:105], v[158:161], v[188:191], v[102:105]
	v_mfma_f32_16x16x32_bf16 v[98:101], v[166:169], v[188:191], v[98:101]
	v_mfma_f32_16x16x32_bf16 v[86:89], v[158:161], v[200:203], v[86:89]
	v_mfma_f32_16x16x32_bf16 v[82:85], v[166:169], v[200:203], v[82:85]
	v_mfma_f32_16x16x32_bf16 v[70:73], v[158:161], v[222:225], v[70:73]
	v_mfma_f32_16x16x32_bf16 v[66:69], v[166:169], v[222:225], v[66:69]
	v_mfma_f32_16x16x32_bf16 v[118:121], v[162:165], v[184:187], v[118:121]
	v_mfma_f32_16x16x32_bf16 v[114:117], v[170:173], v[184:187], v[114:117]
	v_mfma_f32_16x16x32_bf16 v[102:105], v[162:165], v[196:199], v[102:105]
	v_mfma_f32_16x16x32_bf16 v[98:101], v[170:173], v[196:199], v[98:101]
	v_mfma_f32_16x16x32_bf16 v[86:89], v[162:165], v[216:219], v[86:89]
	v_mfma_f32_16x16x32_bf16 v[82:85], v[170:173], v[216:219], v[82:85]
	v_mfma_f32_16x16x32_bf16 v[70:73], v[162:165], v[226:229], v[70:73]
	v_mfma_f32_16x16x32_bf16 v[66:69], v[170:173], v[226:229], v[66:69]
	s_setprio 1
	s_barrier
	s_add_i32 s6, s6, s51
	v_lshl_add_u64 v[192:193], v[192:193], 0, s[98:99]
	s_mov_b32 m0, s6
	ds_read_b128 v[180:183], v147 offset:49152
	ds_read_b128 v[184:187], v147 offset:50176
	ds_read_b128 v[188:191], v147 offset:51200
	ds_read_b128 v[196:199], v147 offset:52224
	ds_read_b128 v[200:203], v147 offset:53248
	ds_read_b128 v[216:219], v147 offset:54272
	ds_read_b128 v[222:225], v147 offset:55296
	ds_read_b128 v[226:229], v147 offset:56320
	global_load_lds_dwordx4 v[192:193], off
	v_lshl_add_u64 v[192:193], v[230:231], 0, s[98:99]
	s_add_i32 m0, s6, 0x2000
	s_add_i32 s6, s56, s51
	global_load_lds_dwordx4 v[192:193], off
	v_lshl_add_u64 v[192:193], v[232:233], 0, s[98:99]
	s_mov_b32 m0, s6
	s_nop 0
	global_load_lds_dwordx4 v[192:193], off
	v_lshl_add_u64 v[192:193], v[234:235], 0, s[98:99]
	s_add_i32 m0, s6, 0x2000
	s_nop 0
	global_load_lds_dwordx4 v[192:193], off
	v_lshl_add_u64 v[192:193], s[90:91], 0, v[148:149]
	s_mov_b32 m0, s82
	s_nop 0
	global_load_lds_dwordx4 v[192:193], off
	v_lshl_add_u64 v[192:193], s[90:91], 0, v[152:153]
	s_mov_b32 m0, s94
	s_nop 0
	global_load_lds_dwordx4 v[192:193], off
	s_waitcnt vmcnt(8)
	s_waitcnt lgkmcnt(0)
	s_barrier
	s_setprio 1
	s_waitcnt lgkmcnt(0)
	v_mfma_f32_16x16x32_bf16 v[62:65], v[130:133], v[180:183], v[62:65]
	v_mfma_f32_16x16x32_bf16 v[58:61], v[138:141], v[180:183], v[58:61]
	v_mfma_f32_16x16x32_bf16 v[46:49], v[130:133], v[188:191], v[46:49]
	v_mfma_f32_16x16x32_bf16 v[42:45], v[138:141], v[188:191], v[42:45]
	v_mfma_f32_16x16x32_bf16 v[30:33], v[130:133], v[200:203], v[30:33]
	v_mfma_f32_16x16x32_bf16 v[26:29], v[138:141], v[200:203], v[26:29]
	v_mfma_f32_16x16x32_bf16 v[14:17], v[130:133], v[222:225], v[14:17]
	v_mfma_f32_16x16x32_bf16 v[10:13], v[138:141], v[222:225], v[10:13]
	v_mfma_f32_16x16x32_bf16 v[62:65], v[134:137], v[184:187], v[62:65]
	v_mfma_f32_16x16x32_bf16 v[58:61], v[142:145], v[184:187], v[58:61]
	v_mfma_f32_16x16x32_bf16 v[46:49], v[134:137], v[196:199], v[46:49]
	v_mfma_f32_16x16x32_bf16 v[42:45], v[142:145], v[196:199], v[42:45]
	v_mfma_f32_16x16x32_bf16 v[30:33], v[134:137], v[216:219], v[30:33]
	v_mfma_f32_16x16x32_bf16 v[26:29], v[142:145], v[216:219], v[26:29]
	v_mfma_f32_16x16x32_bf16 v[14:17], v[134:137], v[226:229], v[14:17]
	v_mfma_f32_16x16x32_bf16 v[10:13], v[142:145], v[226:229], v[10:13]
	s_setprio 1
	s_setprio 1
	v_mfma_f32_16x16x32_bf16 v[54:57], v[158:161], v[180:183], v[54:57]
	v_mfma_f32_16x16x32_bf16 v[50:53], v[166:169], v[180:183], v[50:53]
	v_mfma_f32_16x16x32_bf16 v[38:41], v[158:161], v[188:191], v[38:41]
	v_mfma_f32_16x16x32_bf16 v[34:37], v[166:169], v[188:191], v[34:37]
	v_mfma_f32_16x16x32_bf16 v[22:25], v[158:161], v[200:203], v[22:25]
	v_mfma_f32_16x16x32_bf16 v[18:21], v[166:169], v[200:203], v[18:21]
	v_mfma_f32_16x16x32_bf16 v[6:9], v[158:161], v[222:225], v[6:9]
	v_mfma_f32_16x16x32_bf16 v[2:5], v[166:169], v[222:225], v[2:5]
	v_mfma_f32_16x16x32_bf16 v[54:57], v[162:165], v[184:187], v[54:57]
	v_mfma_f32_16x16x32_bf16 v[50:53], v[170:173], v[184:187], v[50:53]
	v_mfma_f32_16x16x32_bf16 v[38:41], v[162:165], v[196:199], v[38:41]
	v_mfma_f32_16x16x32_bf16 v[34:37], v[170:173], v[196:199], v[34:37]
	v_mfma_f32_16x16x32_bf16 v[22:25], v[162:165], v[216:219], v[22:25]
	v_mfma_f32_16x16x32_bf16 v[18:21], v[170:173], v[216:219], v[18:21]
	v_mfma_f32_16x16x32_bf16 v[6:9], v[162:165], v[226:229], v[6:9]
	v_mfma_f32_16x16x32_bf16 v[2:5], v[170:173], v[226:229], v[2:5]
	s_setprio 1
	s_barrier
	s_add_u32 s64, s64, 0x100
	s_addc_u32 s69, s69, 0
	s_cmp_ge_u32 vcc_lo, s1
	s_mov_b64 s[90:91], vcc
	s_cbranch_scc0 .Lgemm_h1
	s_setprio 0
.Lgemm_join:
	s_and_b64 vcc, exec, s[74:75]
	s_cbranch_vccz .LBB0_349
	s_barrier
